# XCD leader waits only for its L1 invalidate (vmcnt(1)) after the generation bump at sites a-d; site c compare monotonic
# speedup vs baseline: 1.0117x; 1.0117x over previous
.Lloc_d:
	v_readlane_b32 s2, v252, 49
	v_readlane_b32 s3, v252, 50
	s_waitcnt vmcnt(0)
	buffer_inv sc1
	s_nop 2
	global_atomic_add v197, v223, s[2:3]
	s_waitcnt vmcnt(1)
	s_branch .LBB0_125
.Lgb_d:
	v_readlane_b32 s2, v252, 49
	v_readlane_b32 s3, v252, 50
	s_waitcnt vmcnt(0)
	buffer_inv sc1
	s_nop 2
	global_atomic_add v197, v223, s[2:3]
	s_waitcnt vmcnt(1)
.LBB0_125:
	s_or_b64 exec, exec, s[6:7]
	s_waitcnt lgkmcnt(0)
	s_barrier

.Lloc_a:
	v_readlane_b32 s2, v252, 49
	v_readlane_b32 s3, v252, 50
	s_waitcnt vmcnt(0)
	buffer_inv sc1
	s_nop 2
	global_atomic_add v197, v223, s[2:3]
	s_waitcnt vmcnt(1)
	s_branch .LBB0_617
.Lgb_a:
	v_readlane_b32 s2, v252, 49
	v_readlane_b32 s3, v252, 50
	s_waitcnt vmcnt(0)
	buffer_inv sc1
	s_nop 2
	global_atomic_add v197, v223, s[2:3]
	s_waitcnt vmcnt(1)
.LBB0_617:
	s_or_b64 exec, exec, s[6:7]
	s_waitcnt lgkmcnt(0)
	s_barrier

.Lloc_b:
	v_readlane_b32 s2, v252, 49
	v_readlane_b32 s3, v252, 50
	s_waitcnt vmcnt(0)
	buffer_inv sc1
	s_nop 2
	global_atomic_add v197, v223, s[2:3]
	s_waitcnt vmcnt(1)
	s_branch .LBB0_671
.Lgb_b:
	v_readlane_b32 s2, v252, 49
	v_readlane_b32 s3, v252, 50
	s_waitcnt vmcnt(0)
	buffer_inv sc1
	s_nop 2
	global_atomic_add v197, v223, s[2:3]
	s_waitcnt vmcnt(1)
.LBB0_671:
	s_or_b64 exec, exec, s[6:7]
	s_waitcnt lgkmcnt(0)
	s_barrier

.LBB0_831:
	s_or_b64 exec, exec, s[8:9]
	v_readlane_b32 s2, v252, 49
	v_readlane_b32 s3, v252, 50
	s_waitcnt vmcnt(0)
	buffer_inv sc1
	s_nop 2
	global_atomic_add v197, v223, s[2:3]
	s_waitcnt vmcnt(1)
